# P7c accumulating dot products use the VOP2 v_dot4c form (4-byte encoding) instead of VOP3P v_dot4
# speedup vs baseline: 1.0098x; 1.0057x over previous
; #define P7C_LOADA(R0, R1, C, S, X, t) do { const int tt_ = (t) < NT_TOK ? (t) : NT_TOK - 1; const unsigned char* rp_ = rp0 + (size_t)tt_ * 256; R0 = *(const v4u*)rp_; R1 = *(const v4u*)(rp_ + 16); \
;             C = *(const v4u*)(cp0 + (size_t)tt_ * 128); S = SCQ[tt_]; X = *(const unsigned*)(X2Bw + (size_t)tt_ * DM + 128 * hs + 16 * seg + 2 * r); } while (0)
; #define P7C_ISSUE(G, R0, R1) do { __builtin_amdgcn_s_setprio(3); _Pragma("unroll") for (int i_ = 0; i_ < 16; ++i_) { const unsigned e_ = P7_EID(R0, R1, i_); G[i_] = *(const v4u*)(Vb + (size_t)e_ * 128); } __builtin_amdgcn_s_setprio(0); } while (0)
; __device__ __forceinline__ void p7c_vaxpy(Frame& F, unsigned* bar, unsigned x, unsigned rank) {
;     ...
;         v4u GA[16], GB[16], ra0, ra1, ca, rb0, rb1, cb, cA, cB; float sa, sb, sA, sB; unsigned xa, xb2, xA, xB;
;         P7C_LOADA(ra0, ra1, ca, sa, xa, gwl);
;         P7C_LOADA(rb0, rb1, cb, sb, xb2, gwl + stride);
;         P7C_ISSUE(GA, ra0, ra1); cA = ca; sA = sa; xA = xa;
; #pragma unroll 1
;         for (int t = gwl; t < NT_TOK; t += 2 * stride) {
;             P7C_LOADA(ra0, ra1, ca, sa, xa, t + 2 * stride); P7C_ISSUE(GB, rb0, rb1); cB = cb; sB = sb; xB = xb2; P7C_COMP(GA, cA, sA, xA, t);
;             P7C_LOADA(rb0, rb1, cb, sb, xb2, t + 3 * stride); P7C_ISSUE(GA, ra0, ra1); cA = ca; sA = sa; xA = xa; P7C_COMP(GB, cB, sB, xB, t + stride);
.LBB0_1089:
	s_add_i32 s27, s20, s10
	s_min_i32 s18, s27, 0x5fff
	s_ashr_i32 s19, s18, 31
	s_waitcnt vmcnt(22)
	ds_read_b128 v[220:223], v18 offset:256
	s_lshl_b64 s[28:29], s[18:19], 8
	ds_read_b128 v[224:227], v18 offset:272
	s_waitcnt lgkmcnt(0)
	s_add_i32 m0, s59, 0x0
	s_add_u32 s28, s28, s60
	s_addc_u32 s29, s29, s61
	global_load_lds_dword v16, s[28:29]
	s_lshl_b64 s[28:29], s[18:19], 7
	s_add_i32 m0, s59, 0x100
	s_add_u32 s28, s28, s82
	s_addc_u32 s29, s29, s83
	global_load_lds_dword v16, s[28:29]
	s_lshl_b64 s[28:29], s[18:19], 2
	s_add_u32 s28, s54, s28
	s_addc_u32 s29, s55, s29
	s_lshl_b64 s[18:19], s[18:19], 12
	s_waitcnt vmcnt(20)
	v_mov_b32_e32 v206, v197
	v_mov_b32_e32 v207, v196
	v_lshl_add_u64 v[80:81], v[182:183], 0, s[18:19]
	s_nop 0
	global_load_dword v196, v157, s[28:29]
	global_load_dword v197, v[80:81], off
	s_waitcnt vmcnt(16)
	ds_read_b128 v[76:79], v17 offset:512
	ds_read_b128 v[64:67], v17 offset:528
	ds_read_b64_tr_b8 v[240:241], v212
	ds_read_b64_tr_b8 v[242:243], v213
	ds_read_b64_tr_b8 v[244:245], v214
	ds_read_b64_tr_b8 v[246:247], v215
	ds_read_b64_tr_b8 v[248:249], v216
	ds_read_b64_tr_b8 v[250:251], v217
	ds_read_b64_tr_b8 v[252:253], v218
	ds_read_b64_tr_b8 v[228:229], v219
	s_waitcnt lgkmcnt(4)
	s_waitcnt vmcnt(12)
	ds_read_b64_tr_b8 v[48:49], v212 offset:4096
	ds_read_b64_tr_b8 v[50:51], v213 offset:4096
	ds_read_b64_tr_b8 v[52:53], v214 offset:4096
	ds_read_b64_tr_b8 v[54:55], v215 offset:4096
	v_dot4_i32_i8 v232, v240, v220, 0
	v_dot4_i32_i8 v233, v242, v220, 0
	v_dot4_i32_i8 v234, v244, v220, 0
	v_dot4_i32_i8 v235, v246, v220, 0
	v_dot4c_i32_i8_e32 v232, v241, v224
	v_dot4c_i32_i8_e32 v233, v243, v224
	v_dot4c_i32_i8_e32 v234, v245, v224
	v_dot4c_i32_i8_e32 v235, v247, v224
	s_waitcnt lgkmcnt(4)
	s_setprio 3
	v_permlane32_swap_b32_e32 v104, v108
	v_mad_u32_u16 v80, v76, s58, v200 op_sel:[0,0,0,0]
	v_permlane32_swap_b32_e32 v105, v109
	v_mad_u32_u16 v82, v76, s58, v201 op_sel:[1,0,0,0]
	v_permlane32_swap_b32_e32 v106, v110
	s_add_i32 m0, s97, 0x0
	v_permlane32_swap_b32_e32 v107, v111
	s_nop 0
	v_add_u32_e32 v104, v104, v108
	global_load_lds_dwordx4 v80, s[56:57]
	v_add_u32_e32 v105, v105, v109
	s_add_i32 m0, s97, 0x400
	v_add_u32_e32 v106, v106, v110
	s_nop 0
	v_add_u32_e32 v107, v107, v111
	global_load_lds_dwordx4 v82, s[56:57]
	s_nop 1
	v_mad_u32_u16 v80, v77, s58, v202 op_sel:[0,0,0,0]
	v_permlane16_swap_b32_e32 v104, v106
	v_mad_u32_u16 v76, v77, s58, v203 op_sel:[1,0,0,0]
	v_permlane16_swap_b32_e32 v105, v107
	s_add_i32 m0, s97, 0x800
	v_add_u32_e32 v104, v104, v106
	s_nop 0
	v_add_u32_e32 v105, v105, v107
	global_load_lds_dwordx4 v80, s[56:57]
	s_nop 1
	s_add_i32 m0, s97, 0xc00
	v_mov_b32_dpp v106, v104 quad_perm:[1,0,3,2] row_mask:0xf bank_mask:0xf
	s_nop 0
	v_mov_b32_dpp v107, v105 quad_perm:[1,0,3,2] row_mask:0xf bank_mask:0xf
	global_load_lds_dwordx4 v76, s[56:57]
	s_setprio 0
	ds_read_b64_tr_b8 v[240:241], v216 offset:4096
	ds_read_b64_tr_b8 v[242:243], v217 offset:4096
	ds_read_b64_tr_b8 v[244:245], v218 offset:4096
	ds_read_b64_tr_b8 v[246:247], v219 offset:4096
	v_dot4_i32_i8 v236, v248, v220, 0
	v_dot4_i32_i8 v237, v250, v220, 0
	v_dot4_i32_i8 v238, v252, v220, 0
	v_dot4_i32_i8 v239, v228, v220, 0
	v_dot4c_i32_i8_e32 v236, v249, v224
	v_dot4c_i32_i8_e32 v237, v251, v224
	v_dot4c_i32_i8_e32 v238, v253, v224
	v_dot4c_i32_i8_e32 v239, v229, v224
	s_waitcnt lgkmcnt(4)
	s_waitcnt vmcnt(12)
	ds_read_b64_tr_b8 v[248:249], v212 offset:8192
	ds_read_b64_tr_b8 v[250:251], v213 offset:8192
	ds_read_b64_tr_b8 v[252:253], v214 offset:8192
	ds_read_b64_tr_b8 v[228:229], v215 offset:8192
	v_dot4c_i32_i8_e32 v232, v48, v221
	v_dot4c_i32_i8_e32 v233, v50, v221
	v_dot4c_i32_i8_e32 v234, v52, v221
	v_dot4c_i32_i8_e32 v235, v54, v221
	v_dot4c_i32_i8_e32 v232, v49, v225
	v_dot4c_i32_i8_e32 v233, v51, v225
	v_dot4c_i32_i8_e32 v234, v53, v225
	v_dot4c_i32_i8_e32 v235, v55, v225
	s_waitcnt lgkmcnt(4)
	s_setprio 3
	v_cndmask_b32_e64 v108, v107, v104, s[44:45]
	v_mad_u32_u16 v76, v78, s58, v200 op_sel:[0,0,0,0]
	v_cndmask_b32_e64 v109, v105, v106, s[44:45]
	v_mad_u32_u16 v80, v78, s58, v201 op_sel:[1,0,0,0]
	v_cvt_f32_i32_e32 v108, v108
	s_add_i32 m0, s97, 0x1000
	v_cvt_f32_i32_e32 v109, v109
	s_nop 0
	v_lshlrev_b32_e32 v110, 16, v204
	global_load_lds_dwordx4 v76, s[56:57]
	v_and_b32_e32 v111, 0xffff0000, v204
	s_add_i32 m0, s97, 0x1400
	v_fmac_f32_e32 v110, v205, v108
	s_nop 0
	v_fmac_f32_e32 v111, v205, v109
	global_load_lds_dwordx4 v80, s[56:57]
	v_mul_f32_e32 v115, v111, v111
	v_mad_u32_u16 v76, v79, s58, v202 op_sel:[0,0,0,0]
	v_fmac_f32_e32 v115, v110, v110
	v_mad_u32_u16 v78, v79, s58, v203 op_sel:[1,0,0,0]
	v_cvt_pk_bf16_f32 v117, v110, v111
	s_add_i32 m0, s97, 0x1800
	s_cmpk_gt_i32 s98, 0x5fff
	s_cbranch_scc1 .Lp7c_sk1_b
	s_ashr_i32 s99, s98, 31
	s_lshl_b64 s[100:101], s[98:99], 12
	v_lshl_add_u64 v[118:119], v[182:183], 0, s[100:101]
	global_store_dword v[118:119], v117, off
.Lp7c_sk1_b:
	s_nop 0
	s_nop 1
	global_load_lds_dwordx4 v76, s[56:57]
	v_add_f32_dpp v115, v115, v115 quad_perm:[1,0,3,2] row_mask:0xf bank_mask:0xf
	s_add_i32 m0, s97, 0x1c00
	s_nop 1
	s_nop 0
	v_add_f32_dpp v115, v115, v115 quad_perm:[2,3,0,1] row_mask:0xf bank_mask:0xf
	global_load_lds_dwordx4 v78, s[56:57]
	s_setprio 0
	ds_read_b64_tr_b8 v[48:49], v216 offset:8192
	ds_read_b64_tr_b8 v[50:51], v217 offset:8192
	ds_read_b64_tr_b8 v[52:53], v218 offset:8192
	ds_read_b64_tr_b8 v[54:55], v219 offset:8192
	v_dot4c_i32_i8_e32 v236, v240, v221
	v_dot4c_i32_i8_e32 v237, v242, v221
	v_dot4c_i32_i8_e32 v238, v244, v221
	v_dot4c_i32_i8_e32 v239, v246, v221
	v_dot4c_i32_i8_e32 v236, v241, v225
	v_dot4c_i32_i8_e32 v237, v243, v225
	v_dot4c_i32_i8_e32 v238, v245, v225
	v_dot4c_i32_i8_e32 v239, v247, v225
	s_waitcnt lgkmcnt(4)
	s_waitcnt vmcnt(12)
	ds_read_b64_tr_b8 v[240:241], v212 offset:12288
	ds_read_b64_tr_b8 v[242:243], v213 offset:12288
	ds_read_b64_tr_b8 v[244:245], v214 offset:12288
	ds_read_b64_tr_b8 v[246:247], v215 offset:12288
	v_dot4c_i32_i8_e32 v232, v248, v222
	v_dot4c_i32_i8_e32 v233, v250, v222
	v_dot4c_i32_i8_e32 v234, v252, v222
	v_dot4c_i32_i8_e32 v235, v228, v222
	v_dot4c_i32_i8_e32 v232, v249, v226
	v_dot4c_i32_i8_e32 v233, v251, v226
	v_dot4c_i32_i8_e32 v234, v253, v226
	v_dot4c_i32_i8_e32 v235, v229, v226
	s_waitcnt lgkmcnt(4)
	s_setprio 3
	s_nop 1
	v_mad_u32_u16 v76, v64, s58, v200 op_sel:[0,0,0,0]
	v_add_f32_dpp v115, v115, v115 row_half_mirror row_mask:0xf bank_mask:0xf
	v_mad_u32_u16 v78, v64, s58, v201 op_sel:[1,0,0,0]
	s_nop 1
	s_add_i32 m0, s97, 0x2000
	v_add_f32_dpp v115, v115, v115 row_mirror row_mask:0xf bank_mask:0xf
	s_nop 0
	v_mov_b32_e32 v116, v115
	global_load_lds_dwordx4 v76, s[56:57]
	s_nop 1
	s_add_i32 m0, s97, 0x2400
	v_permlane16_swap_b32_e32 v115, v116
	s_nop 0
	v_add_f32_e32 v115, v115, v116
	global_load_lds_dwordx4 v78, s[56:57]
	v_mov_b32_e32 v116, v115
	v_mad_u32_u16 v76, v65, s58, v202 op_sel:[0,0,0,0]
	s_nop 1
	v_mad_u32_u16 v64, v65, s58, v203 op_sel:[1,0,0,0]
	v_permlane32_swap_b32_e32 v115, v116
	s_add_i32 m0, s97, 0x2800
	v_add_f32_e32 v115, v115, v116
	s_nop 0
	s_cmpk_gt_i32 s98, 0x5fff
	s_cbranch_scc1 .Lp7c_sk2_b
	s_ashr_i32 s99, s98, 31
	s_lshl_b64 s[100:101], s[98:99], 6
	v_lshl_add_u64 v[118:119], v[184:185], 0, s[100:101]
	s_and_saveexec_b64 s[18:19], s[42:43]
	global_store_dword v[118:119], v115, off
	s_mov_b64 exec, s[18:19]
.Lp7c_sk2_b:
	global_load_lds_dwordx4 v76, s[56:57]
	s_add_i32 m0, s97, 0x2c00
	s_nop 0
	global_load_lds_dwordx4 v64, s[56:57]
	s_setprio 0
	ds_read_b64_tr_b8 v[248:249], v216 offset:12288
	ds_read_b64_tr_b8 v[250:251], v217 offset:12288
	ds_read_b64_tr_b8 v[252:253], v218 offset:12288
	ds_read_b64_tr_b8 v[228:229], v219 offset:12288
	v_dot4c_i32_i8_e32 v236, v48, v222
	v_dot4c_i32_i8_e32 v237, v50, v222
	v_dot4c_i32_i8_e32 v238, v52, v222
	v_dot4c_i32_i8_e32 v239, v54, v222
	v_dot4c_i32_i8_e32 v236, v49, v226
	v_dot4c_i32_i8_e32 v237, v51, v226
	v_dot4c_i32_i8_e32 v238, v53, v226
	v_dot4c_i32_i8_e32 v239, v55, v226
	s_waitcnt lgkmcnt(4)
	v_dot4c_i32_i8_e32 v232, v240, v223
	v_dot4c_i32_i8_e32 v233, v242, v223
	v_dot4c_i32_i8_e32 v234, v244, v223
	v_dot4c_i32_i8_e32 v235, v246, v223
	v_dot4c_i32_i8_e32 v232, v241, v227
	v_dot4c_i32_i8_e32 v233, v243, v227
	v_dot4c_i32_i8_e32 v234, v245, v227
	v_dot4c_i32_i8_e32 v235, v247, v227
	s_waitcnt lgkmcnt(0)
	s_setprio 3
	v_mad_u32_u16 v64, v66, s58, v200 op_sel:[0,0,0,0]
	v_mad_u32_u16 v76, v66, s58, v201 op_sel:[1,0,0,0]
	s_add_i32 m0, s97, 0x3000
	s_nop 0
	global_load_lds_dwordx4 v64, s[56:57]
	s_add_i32 m0, s97, 0x3400
	s_nop 0
	global_load_lds_dwordx4 v76, s[56:57]
	v_mad_u32_u16 v64, v67, s58, v202 op_sel:[0,0,0,0]
	v_mad_u32_u16 v66, v67, s58, v203 op_sel:[1,0,0,0]
	s_add_i32 m0, s97, 0x3800
	s_nop 0
	global_load_lds_dwordx4 v64, s[56:57]
	s_add_i32 m0, s97, 0x3c00
	s_nop 0
	global_load_lds_dwordx4 v66, s[56:57]
	s_setprio 0
	v_dot4c_i32_i8_e32 v236, v248, v223
	v_dot4c_i32_i8_e32 v237, v250, v223
	v_dot4c_i32_i8_e32 v238, v252, v223
	v_dot4c_i32_i8_e32 v239, v228, v223
	v_dot4c_i32_i8_e32 v236, v249, v227
	v_dot4c_i32_i8_e32 v237, v251, v227
	v_dot4c_i32_i8_e32 v238, v253, v227
	v_dot4c_i32_i8_e32 v239, v229, v227
	v_mov_b32_e32 v204, v206
	v_mov_b32_e32 v205, v207
	s_add_i32 s18, s24, s20
	s_min_i32 s18, s18, 0x5fff
	s_ashr_i32 s19, s18, 31
	s_lshl_b64 s[28:29], s[18:19], 8
	s_waitcnt lgkmcnt(0)
	s_waitcnt vmcnt(24)
	ds_read_b128 v[220:223], v18 offset:768
	ds_read_b128 v[224:227], v18 offset:784
	s_waitcnt lgkmcnt(0)
	s_add_i32 m0, s59, 0x200
	s_add_u32 s28, s28, s60
	s_addc_u32 s29, s29, s61
	global_load_lds_dword v16, s[28:29]
	s_lshl_b64 s[28:29], s[18:19], 7
	s_add_i32 m0, s59, 0x300
	s_add_u32 s28, s28, s82
	s_addc_u32 s29, s29, s83
	global_load_lds_dword v16, s[28:29]
	s_lshl_b64 s[28:29], s[18:19], 2
	s_add_u32 s28, s54, s28
	s_addc_u32 s29, s55, s29
	s_lshl_b64 s[18:19], s[18:19], 12
	v_lshl_add_u64 v[10:11], v[182:183], 0, s[18:19]
	global_load_dword v207, v157, s[28:29]
	global_load_dword v206, v[10:11], off
	s_waitcnt vmcnt(16)
	ds_read_b128 v[148:151], v17
	ds_read_b128 v[144:147], v17 offset:16
	ds_read_b64_tr_b8 v[240:241], v212
	ds_read_b64_tr_b8 v[242:243], v213
	ds_read_b64_tr_b8 v[244:245], v214
	ds_read_b64_tr_b8 v[246:247], v215
	ds_read_b64_tr_b8 v[248:249], v216
	ds_read_b64_tr_b8 v[250:251], v217
	ds_read_b64_tr_b8 v[252:253], v218
	ds_read_b64_tr_b8 v[228:229], v219
	s_waitcnt lgkmcnt(4)
	s_waitcnt vmcnt(12)
	ds_read_b64_tr_b8 v[128:129], v212 offset:4096
	ds_read_b64_tr_b8 v[130:131], v213 offset:4096
	ds_read_b64_tr_b8 v[132:133], v214 offset:4096
	ds_read_b64_tr_b8 v[134:135], v215 offset:4096
	v_dot4_i32_i8 v104, v240, v220, 0
	v_dot4_i32_i8 v105, v242, v220, 0
	v_dot4_i32_i8 v106, v244, v220, 0
	v_dot4_i32_i8 v107, v246, v220, 0
	v_dot4c_i32_i8_e32 v104, v241, v224
	v_dot4c_i32_i8_e32 v105, v243, v224
	v_dot4c_i32_i8_e32 v106, v245, v224
	v_dot4c_i32_i8_e32 v107, v247, v224
	s_waitcnt lgkmcnt(4)
	s_setprio 3
	v_permlane32_swap_b32_e32 v232, v236
	v_mad_u32_u16 v8, v148, s58, v200 op_sel:[0,0,0,0]
	v_permlane32_swap_b32_e32 v233, v237
	v_mad_u32_u16 v10, v148, s58, v201 op_sel:[1,0,0,0]
	v_permlane32_swap_b32_e32 v234, v238
	s_add_i32 m0, s97, 0x0
	v_permlane32_swap_b32_e32 v235, v239
	s_nop 0
	v_add_u32_e32 v232, v232, v236
	global_load_lds_dwordx4 v8, s[56:57]
	v_add_u32_e32 v233, v233, v237
	s_add_i32 m0, s97, 0x400
	v_add_u32_e32 v234, v234, v238
	s_nop 0
	v_add_u32_e32 v235, v235, v239
	global_load_lds_dwordx4 v10, s[56:57]
	s_nop 1
	v_mad_u32_u16 v8, v149, s58, v202 op_sel:[0,0,0,0]
	v_permlane16_swap_b32_e32 v232, v234
	v_mad_u32_u16 v10, v149, s58, v203 op_sel:[1,0,0,0]
	v_permlane16_swap_b32_e32 v233, v235
	s_add_i32 m0, s97, 0x800
	v_add_u32_e32 v232, v232, v234
	s_nop 0
	v_add_u32_e32 v233, v233, v235
	global_load_lds_dwordx4 v8, s[56:57]
	s_nop 1
	s_add_i32 m0, s97, 0xc00
	v_mov_b32_dpp v234, v232 quad_perm:[1,0,3,2] row_mask:0xf bank_mask:0xf
	s_nop 0
	v_mov_b32_dpp v235, v233 quad_perm:[1,0,3,2] row_mask:0xf bank_mask:0xf
	global_load_lds_dwordx4 v10, s[56:57]
	s_setprio 0
	ds_read_b64_tr_b8 v[240:241], v216 offset:4096
	ds_read_b64_tr_b8 v[242:243], v217 offset:4096
	ds_read_b64_tr_b8 v[244:245], v218 offset:4096
	ds_read_b64_tr_b8 v[246:247], v219 offset:4096
	v_dot4_i32_i8 v108, v248, v220, 0
	v_dot4_i32_i8 v109, v250, v220, 0
	v_dot4_i32_i8 v110, v252, v220, 0
	v_dot4_i32_i8 v111, v228, v220, 0
	v_dot4c_i32_i8_e32 v108, v249, v224
	v_dot4c_i32_i8_e32 v109, v251, v224
	v_dot4c_i32_i8_e32 v110, v253, v224
	v_dot4c_i32_i8_e32 v111, v229, v224
	s_waitcnt lgkmcnt(4)
	s_waitcnt vmcnt(12)
	ds_read_b64_tr_b8 v[248:249], v212 offset:8192
	ds_read_b64_tr_b8 v[250:251], v213 offset:8192
	ds_read_b64_tr_b8 v[252:253], v214 offset:8192
	ds_read_b64_tr_b8 v[228:229], v215 offset:8192
	v_dot4c_i32_i8_e32 v104, v128, v221
	v_dot4c_i32_i8_e32 v105, v130, v221
	v_dot4c_i32_i8_e32 v106, v132, v221
	v_dot4c_i32_i8_e32 v107, v134, v221
	v_dot4c_i32_i8_e32 v104, v129, v225
	v_dot4c_i32_i8_e32 v105, v131, v225
	v_dot4c_i32_i8_e32 v106, v133, v225
	v_dot4c_i32_i8_e32 v107, v135, v225
	s_waitcnt lgkmcnt(4)
	s_setprio 3
	v_cndmask_b32_e64 v236, v235, v232, s[44:45]
	v_mad_u32_u16 v8, v150, s58, v200 op_sel:[0,0,0,0]
	v_cndmask_b32_e64 v237, v233, v234, s[44:45]
	v_mad_u32_u16 v10, v150, s58, v201 op_sel:[1,0,0,0]
	v_cvt_f32_i32_e32 v236, v236
	s_add_i32 m0, s97, 0x1000
	v_cvt_f32_i32_e32 v237, v237
	s_nop 0
	v_lshlrev_b32_e32 v238, 16, v204
	global_load_lds_dwordx4 v8, s[56:57]
	v_and_b32_e32 v239, 0xffff0000, v204
	s_add_i32 m0, s97, 0x1400
	v_fmac_f32_e32 v238, v205, v236
	s_nop 0
	v_fmac_f32_e32 v239, v205, v237
	global_load_lds_dwordx4 v10, s[56:57]
	v_mul_f32_e32 v112, v239, v239
	v_mad_u32_u16 v8, v151, s58, v202 op_sel:[0,0,0,0]
	v_fmac_f32_e32 v112, v238, v238
	v_mad_u32_u16 v10, v151, s58, v203 op_sel:[1,0,0,0]
	v_cvt_pk_bf16_f32 v114, v238, v239
	s_add_i32 m0, s97, 0x1800
	global_store_dword v[188:189], v114, off
	s_nop 0
	s_nop 1
	global_load_lds_dwordx4 v8, s[56:57]
	v_add_f32_dpp v112, v112, v112 quad_perm:[1,0,3,2] row_mask:0xf bank_mask:0xf
	s_add_i32 m0, s97, 0x1c00
	s_nop 1
	s_nop 0
	v_add_f32_dpp v112, v112, v112 quad_perm:[2,3,0,1] row_mask:0xf bank_mask:0xf
	global_load_lds_dwordx4 v10, s[56:57]
	s_setprio 0
	ds_read_b64_tr_b8 v[128:129], v216 offset:8192
	ds_read_b64_tr_b8 v[130:131], v217 offset:8192
	ds_read_b64_tr_b8 v[132:133], v218 offset:8192
	ds_read_b64_tr_b8 v[134:135], v219 offset:8192
	v_dot4c_i32_i8_e32 v108, v240, v221
	v_dot4c_i32_i8_e32 v109, v242, v221
	v_dot4c_i32_i8_e32 v110, v244, v221
	v_dot4c_i32_i8_e32 v111, v246, v221
	v_dot4c_i32_i8_e32 v108, v241, v225
	v_dot4c_i32_i8_e32 v109, v243, v225
	v_dot4c_i32_i8_e32 v110, v245, v225
	v_dot4c_i32_i8_e32 v111, v247, v225
	s_waitcnt lgkmcnt(4)
; #define P7C_LOADA(R0, R1, C, S, X, t) do { const int tt_ = (t) < NT_TOK ? (t) : NT_TOK - 1; const unsigned char* rp_ = rp0 + (size_t)tt_ * 256; R0 = *(const v4u*)rp_; R1 = *(const v4u*)(rp_ + 16); \
;             C = *(const v4u*)(cp0 + (size_t)tt_ * 128); S = SCQ[tt_]; X = *(const unsigned*)(X2Bw + (size_t)tt_ * DM + 128 * hs + 16 * seg + 2 * r); } while (0)
; #define P7C_ISSUE(G, R0, R1) do { __builtin_amdgcn_s_setprio(3); _Pragma("unroll") for (int i_ = 0; i_ < 16; ++i_) { const unsigned e_ = P7_EID(R0, R1, i_); G[i_] = *(const v4u*)(Vb + (size_t)e_ * 128); } __builtin_amdgcn_s_setprio(0); } while (0)
; __device__ __forceinline__ void p7c_vaxpy(Frame& F, unsigned* bar, unsigned x, unsigned rank) {
;     ...
;         v4u GA[16], GB[16], ra0, ra1, ca, rb0, rb1, cb, cA, cB; float sa, sb, sA, sB; unsigned xa, xb2, xA, xB;
;         P7C_LOADA(ra0, ra1, ca, sa, xa, gwl);
;         P7C_LOADA(rb0, rb1, cb, sb, xb2, gwl + stride);
;         P7C_ISSUE(GA, ra0, ra1); cA = ca; sA = sa; xA = xa;
; #pragma unroll 1
;         for (int t = gwl; t < NT_TOK; t += 2 * stride) {
;             P7C_LOADA(ra0, ra1, ca, sa, xa, t + 2 * stride); P7C_ISSUE(GB, rb0, rb1); cB = cb; sB = sb; xB = xb2; P7C_COMP(GA, cA, sA, xA, t);
;             P7C_LOADA(rb0, rb1, cb, sb, xb2, t + 3 * stride); P7C_ISSUE(GA, ra0, ra1); cA = ca; sA = sa; xA = xa; P7C_COMP(GB, cB, sB, xB, t + stride);
	s_waitcnt vmcnt(12)
	ds_read_b64_tr_b8 v[240:241], v212 offset:12288
	ds_read_b64_tr_b8 v[242:243], v213 offset:12288
	ds_read_b64_tr_b8 v[244:245], v214 offset:12288
	ds_read_b64_tr_b8 v[246:247], v215 offset:12288
	v_dot4c_i32_i8_e32 v104, v248, v222
	v_dot4c_i32_i8_e32 v105, v250, v222
	v_dot4c_i32_i8_e32 v106, v252, v222
	v_dot4c_i32_i8_e32 v107, v228, v222
	v_dot4c_i32_i8_e32 v104, v249, v226
	v_dot4c_i32_i8_e32 v105, v251, v226
	v_dot4c_i32_i8_e32 v106, v253, v226
	v_dot4c_i32_i8_e32 v107, v229, v226
	s_waitcnt lgkmcnt(4)
	s_setprio 3
	s_nop 1
	v_mad_u32_u16 v8, v144, s58, v200 op_sel:[0,0,0,0]
	v_add_f32_dpp v112, v112, v112 row_half_mirror row_mask:0xf bank_mask:0xf
	v_mad_u32_u16 v10, v144, s58, v201 op_sel:[1,0,0,0]
	s_nop 1
	s_add_i32 m0, s97, 0x2000
	v_add_f32_dpp v112, v112, v112 row_mirror row_mask:0xf bank_mask:0xf
	s_nop 0
	v_mov_b32_e32 v113, v112
	global_load_lds_dwordx4 v8, s[56:57]
	s_nop 1
	s_add_i32 m0, s97, 0x2400
	v_permlane16_swap_b32_e32 v112, v113
	s_nop 0
	v_add_f32_e32 v112, v112, v113
	global_load_lds_dwordx4 v10, s[56:57]
	v_mov_b32_e32 v113, v112
	v_mad_u32_u16 v8, v145, s58, v202 op_sel:[0,0,0,0]
	s_nop 1
	v_mad_u32_u16 v10, v145, s58, v203 op_sel:[1,0,0,0]
	v_permlane32_swap_b32_e32 v112, v113
	s_add_i32 m0, s97, 0x2800
	v_add_f32_e32 v112, v112, v113
	s_nop 0
	s_and_saveexec_b64 s[18:19], s[42:43]
	global_store_dword v[186:187], v112, off
	s_mov_b64 exec, s[18:19]
	global_load_lds_dwordx4 v8, s[56:57]
	s_add_i32 m0, s97, 0x2c00
	s_nop 0
	global_load_lds_dwordx4 v10, s[56:57]
	s_setprio 0
	ds_read_b64_tr_b8 v[248:249], v216 offset:12288
	ds_read_b64_tr_b8 v[250:251], v217 offset:12288
	ds_read_b64_tr_b8 v[252:253], v218 offset:12288
	ds_read_b64_tr_b8 v[228:229], v219 offset:12288
	v_dot4c_i32_i8_e32 v108, v128, v222
	v_dot4c_i32_i8_e32 v109, v130, v222
	v_dot4c_i32_i8_e32 v110, v132, v222
	v_dot4c_i32_i8_e32 v111, v134, v222
	v_dot4c_i32_i8_e32 v108, v129, v226
	v_dot4c_i32_i8_e32 v109, v131, v226
	v_dot4c_i32_i8_e32 v110, v133, v226
	v_dot4c_i32_i8_e32 v111, v135, v226
	s_waitcnt lgkmcnt(4)
	v_dot4c_i32_i8_e32 v104, v240, v223
	v_dot4c_i32_i8_e32 v105, v242, v223
	v_dot4c_i32_i8_e32 v106, v244, v223
	v_dot4c_i32_i8_e32 v107, v246, v223
	v_dot4c_i32_i8_e32 v104, v241, v227
	v_dot4c_i32_i8_e32 v105, v243, v227
	v_dot4c_i32_i8_e32 v106, v245, v227
	v_dot4c_i32_i8_e32 v107, v247, v227
	s_waitcnt lgkmcnt(0)
	s_setprio 3
	v_mad_u32_u16 v8, v146, s58, v200 op_sel:[0,0,0,0]
	v_mad_u32_u16 v12, v146, s58, v201 op_sel:[1,0,0,0]
	v_mad_u32_u16 v24, v147, s58, v202 op_sel:[0,0,0,0]
	v_mad_u32_u16 v28, v147, s58, v203 op_sel:[1,0,0,0]
	s_add_i32 m0, s97, 0x3000
	s_nop 0
	global_load_lds_dwordx4 v8, s[56:57]
	s_nop 0
	s_add_i32 m0, s97, 0x3400
	s_nop 0
	global_load_lds_dwordx4 v12, s[56:57]
	s_nop 0
	s_add_i32 m0, s97, 0x3800
	s_nop 0
	global_load_lds_dwordx4 v24, s[56:57]
	s_nop 0
	s_add_i32 m0, s97, 0x3c00
	s_nop 0
	global_load_lds_dwordx4 v28, s[56:57]
	s_setprio 0
	v_dot4c_i32_i8_e32 v108, v248, v223
	v_dot4c_i32_i8_e32 v109, v250, v223
	v_dot4c_i32_i8_e32 v110, v252, v223
	v_dot4c_i32_i8_e32 v111, v228, v223
	v_dot4c_i32_i8_e32 v108, v249, v227
	v_dot4c_i32_i8_e32 v109, v251, v227
	v_dot4c_i32_i8_e32 v110, v253, v227
	v_dot4c_i32_i8_e32 v111, v229, v227
	v_mov_b32_e32 v204, v199
	v_mov_b32_e32 v205, v198
	s_add_i32 s98, s23, s20
	s_branch .LBB0_1088
